# grid barriers: L1 invalidate issued right after the arrival atomic returns (completes under the wait) instead of after the release is observed; no loads other than sc1 polls happen in between
# speedup vs baseline: 1.0202x; 1.0163x over previous
.LBB0_112:
	s_or_b64 exec, exec, s[24:25]
	v_cvt_f32_u32_e32 v140, v134
	s_waitcnt vmcnt(0)
	buffer_inv sc1
	v_readfirstlane_b32 s22, v135
	v_sub_u32_e32 v135, 0, v134
	v_rcp_iflag_f32_e32 v140, v140
	v_add_u32_e32 v141, s22, v129
	v_mul_f32_e32 v140, 0x4f7ffffe, v140
	v_cvt_u32_f32_e32 v140, v140
	v_mul_lo_u32 v129, v135, v140
	v_mul_hi_u32 v129, v140, v129
	v_add_u32_e32 v129, v140, v129
	v_mul_hi_u32 v129, v141, v129
	v_mul_lo_u32 v135, v129, v134
	v_sub_u32_e32 v135, v141, v135
	v_add_u32_e32 v140, 1, v129
	v_cmp_ge_u32_e32 vcc, v135, v134
	s_nop 1
	v_cndmask_b32_e32 v129, v129, v140, vcc
	v_sub_u32_e32 v140, v135, v134
	v_cndmask_b32_e32 v135, v135, v140, vcc
	v_add_u32_e32 v140, 1, v129
	v_cmp_ge_u32_e32 vcc, v135, v134
	v_add_u32_e32 v135, 1, v141
	s_nop 0
	v_cndmask_b32_e32 v129, v129, v140, vcc
	v_mul_lo_u32 v140, v134, v129
	v_add_u32_e32 v134, v140, v134
	v_cmp_ne_u32_e32 vcc, v135, v134
	s_and_saveexec_b64 s[22:23], vcc
	s_xor_b64 s[22:23], exec, s[22:23]
	s_cbranch_execz .LBB0_126
	s_waitcnt lgkmcnt(0)
	v_mov_b32_e32 v128, 0x2000
	global_load_dword v128, v128, s[6:7] offset:1024 sc1
	s_add_u32 s28, s6, 0x2400
	s_addc_u32 s29, s7, 0
	s_waitcnt vmcnt(0)
	v_cmp_eq_u32_e32 vcc, v128, v129
	s_and_saveexec_b64 s[24:25], vcc
	s_cbranch_execz .LBB0_125
	s_add_u32 s26, s78, 0xefe8a00
	s_addc_u32 s27, s79, 0
	s_mov_b32 s42, 1
	s_mov_b64 s[30:31], 0
	v_mov_b32_e32 v128, 0
	s_branch .LBB0_116

.LBB0_125:
	s_or_b64 exec, exec, s[24:25]
	s_waitcnt vmcnt(0)
	s_waitcnt vmcnt(0)

.LBB0_143:
	s_or_b64 exec, exec, s[22:23]
	s_mov_b64 s[22:23], exec
	v_mbcnt_lo_u32_b32 v128, s22, 0
	v_mbcnt_hi_u32_b32 v128, s23, v128
	v_cmp_eq_u32_e32 vcc, 0, v128
	s_waitcnt vmcnt(0)
	s_and_saveexec_b64 s[24:25], vcc
	s_cbranch_execz .LBB0_145
	s_bcnt1_i32_b64 s22, s[22:23]
	v_mov_b32_e32 v128, 0x2000
	v_mov_b32_e32 v129, s22
	global_atomic_add v128, v129, s[6:7] offset:1024

.LBB0_181:
	s_or_b64 exec, exec, s[8:9]
	v_cvt_f32_u32_e32 v4, v2
	s_waitcnt vmcnt(0)
	buffer_inv sc1
	v_readfirstlane_b32 s6, v3
	v_sub_u32_e32 v3, 0, v2
	v_rcp_iflag_f32_e32 v4, v4
	v_add_u32_e32 v5, s6, v1
	v_mul_f32_e32 v4, 0x4f7ffffe, v4
	v_cvt_u32_f32_e32 v4, v4
	v_mul_lo_u32 v1, v3, v4
	v_mul_hi_u32 v1, v4, v1
	v_add_u32_e32 v1, v4, v1
	v_mul_hi_u32 v1, v5, v1
	v_mul_lo_u32 v3, v1, v2
	v_sub_u32_e32 v3, v5, v3
	v_add_u32_e32 v4, 1, v1
	v_cmp_ge_u32_e32 vcc, v3, v2
	s_nop 1
	v_cndmask_b32_e32 v1, v1, v4, vcc
	v_sub_u32_e32 v4, v3, v2
	v_cndmask_b32_e32 v3, v3, v4, vcc
	v_add_u32_e32 v4, 1, v1
	v_cmp_ge_u32_e32 vcc, v3, v2
	v_add_u32_e32 v3, 1, v5
	s_nop 0
	v_cndmask_b32_e32 v1, v1, v4, vcc
	v_mul_lo_u32 v4, v2, v1
	v_add_u32_e32 v2, v4, v2
	v_cmp_ne_u32_e32 vcc, v3, v2
	s_and_saveexec_b64 s[6:7], vcc
	s_xor_b64 s[6:7], exec, s[6:7]
	s_cbranch_execz .LBB0_195
	s_waitcnt lgkmcnt(0)
	v_mov_b32_e32 v0, 0x2000
	global_load_dword v0, v0, s[4:5] offset:1024 sc1
	s_add_u32 s14, s4, 0x2400
	s_addc_u32 s15, s5, 0
	s_waitcnt vmcnt(0)
	v_cmp_eq_u32_e32 vcc, v0, v1
	s_and_saveexec_b64 s[8:9], vcc
	s_cbranch_execz .LBB0_194
	s_add_u32 s12, s78, 0xefe8a00
	s_addc_u32 s13, s79, 0
	s_mov_b32 s26, 1
	s_mov_b64 s[16:17], 0
	v_mov_b32_e32 v0, 0
	s_branch .LBB0_185

.LBB0_194:
	s_or_b64 exec, exec, s[8:9]
	s_waitcnt vmcnt(0)
	s_waitcnt vmcnt(0)

.LBB0_212:
	s_or_b64 exec, exec, s[6:7]
	s_mov_b64 s[6:7], exec
	v_mbcnt_lo_u32_b32 v0, s6, 0
	v_mbcnt_hi_u32_b32 v0, s7, v0
	v_cmp_eq_u32_e32 vcc, 0, v0
	s_waitcnt vmcnt(0)
	s_and_saveexec_b64 s[8:9], vcc
	s_cbranch_execz .LBB0_214
	s_bcnt1_i32_b64 s6, s[6:7]
	v_mov_b32_e32 v0, 0x2000
	v_mov_b32_e32 v1, s6
	global_atomic_add v0, v1, s[4:5] offset:1024

.LBB0_560:
	s_or_b64 exec, exec, s[6:7]
	v_cvt_f32_u32_e32 v4, v2
	s_waitcnt vmcnt(0)
	buffer_inv sc1
	v_readfirstlane_b32 s4, v3
	v_sub_u32_e32 v3, 0, v2
	v_rcp_iflag_f32_e32 v4, v4
	v_add_u32_e32 v5, s4, v1
	v_mul_f32_e32 v4, 0x4f7ffffe, v4
	v_cvt_u32_f32_e32 v4, v4
	v_mul_lo_u32 v1, v3, v4
	v_mul_hi_u32 v1, v4, v1
	v_add_u32_e32 v1, v4, v1
	v_mul_hi_u32 v1, v5, v1
	v_mul_lo_u32 v3, v1, v2
	v_sub_u32_e32 v3, v5, v3
	v_add_u32_e32 v4, 1, v1
	v_cmp_ge_u32_e32 vcc, v3, v2
	s_nop 1
	v_cndmask_b32_e32 v1, v1, v4, vcc
	v_sub_u32_e32 v4, v3, v2
	v_cndmask_b32_e32 v3, v3, v4, vcc
	v_add_u32_e32 v4, 1, v1
	v_cmp_ge_u32_e32 vcc, v3, v2
	v_add_u32_e32 v3, 1, v5
	s_nop 0
	v_cndmask_b32_e32 v1, v1, v4, vcc
	v_mul_lo_u32 v4, v2, v1
	v_add_u32_e32 v2, v4, v2
	v_cmp_ne_u32_e32 vcc, v3, v2
	s_and_saveexec_b64 s[4:5], vcc
	s_xor_b64 s[4:5], exec, s[4:5]
	s_cbranch_execz .LBB0_574
	s_waitcnt lgkmcnt(0)
	global_load_dword v0, v160, s[2:3] offset:1024 sc1
	s_add_u32 s8, s2, 0x2400
	s_addc_u32 s9, s3, 0
	s_waitcnt vmcnt(0)
	v_cmp_eq_u32_e32 vcc, v0, v1
	s_and_saveexec_b64 s[6:7], vcc
	s_cbranch_execz .LBB0_573
	s_mov_b32 s12, 1
	s_mov_b64 s[14:15], 0
	s_branch .LBB0_564

.LBB0_573:
	s_or_b64 exec, exec, s[6:7]
	s_waitcnt vmcnt(0)
	s_waitcnt vmcnt(0)

.LBB0_591:
	s_or_b64 exec, exec, s[4:5]
	s_mov_b64 s[4:5], exec
	v_mbcnt_lo_u32_b32 v0, s4, 0
	v_mbcnt_hi_u32_b32 v0, s5, v0
	v_cmp_eq_u32_e32 vcc, 0, v0
	s_waitcnt vmcnt(0)
	s_and_saveexec_b64 s[6:7], vcc
	s_cbranch_execz .LBB0_216
	s_bcnt1_i32_b64 s4, s[4:5]
	v_mov_b32_e32 v0, s4
	global_atomic_add v160, v0, s[2:3] offset:1024
	s_branch .LBB0_216

.LBB0_765:
	s_or_b64 exec, exec, s[8:9]
	v_cvt_f32_u32_e32 v4, v2
	s_waitcnt vmcnt(0)
	buffer_inv sc1
	v_readfirstlane_b32 s6, v3
	v_sub_u32_e32 v3, 0, v2
	v_rcp_iflag_f32_e32 v4, v4
	v_add_u32_e32 v5, s6, v1
	v_mul_f32_e32 v4, 0x4f7ffffe, v4
	v_cvt_u32_f32_e32 v4, v4
	v_mul_lo_u32 v1, v3, v4
	v_mul_hi_u32 v1, v4, v1
	v_add_u32_e32 v1, v4, v1
	v_mul_hi_u32 v1, v5, v1
	v_mul_lo_u32 v3, v1, v2
	v_sub_u32_e32 v3, v5, v3
	v_add_u32_e32 v4, 1, v1
	v_cmp_ge_u32_e32 vcc, v3, v2
	s_nop 1
	v_cndmask_b32_e32 v1, v1, v4, vcc
	v_sub_u32_e32 v4, v3, v2
	v_cndmask_b32_e32 v3, v3, v4, vcc
	v_add_u32_e32 v4, 1, v1
	v_cmp_ge_u32_e32 vcc, v3, v2
	v_add_u32_e32 v3, 1, v5
	s_nop 0
	v_cndmask_b32_e32 v1, v1, v4, vcc
	v_mul_lo_u32 v4, v2, v1
	v_add_u32_e32 v2, v4, v2
	v_cmp_ne_u32_e32 vcc, v3, v2
	s_and_saveexec_b64 s[6:7], vcc
	s_xor_b64 s[6:7], exec, s[6:7]
	s_cbranch_execz .LBB0_779
	s_waitcnt lgkmcnt(0)
	v_mov_b32_e32 v0, 0x2000
	global_load_dword v0, v0, s[4:5] offset:1024 sc1
	s_add_u32 s14, s4, 0x2400
	s_addc_u32 s15, s5, 0
	s_waitcnt vmcnt(0)
	v_cmp_eq_u32_e32 vcc, v0, v1
	s_and_saveexec_b64 s[8:9], vcc
	s_cbranch_execz .LBB0_778
	s_mov_b32 s12, 1
	s_mov_b64 s[16:17], 0
	v_mov_b32_e32 v0, 0
	s_branch .LBB0_769

.LBB0_840:
	s_or_b64 exec, exec, s[8:9]
	v_cvt_f32_u32_e32 v4, v2
	s_waitcnt vmcnt(0)
	buffer_inv sc1
	v_readfirstlane_b32 s4, v3
	v_sub_u32_e32 v3, 0, v2
	v_rcp_iflag_f32_e32 v4, v4
	v_add_u32_e32 v5, s4, v1
	v_mul_f32_e32 v4, 0x4f7ffffe, v4
	v_cvt_u32_f32_e32 v4, v4
	v_mul_lo_u32 v1, v3, v4
	v_mul_hi_u32 v1, v4, v1
	v_add_u32_e32 v1, v4, v1
	v_mul_hi_u32 v1, v5, v1
	v_mul_lo_u32 v3, v1, v2
	v_sub_u32_e32 v3, v5, v3
	v_add_u32_e32 v4, 1, v1
	v_cmp_ge_u32_e32 vcc, v3, v2
	s_nop 1
	v_cndmask_b32_e32 v1, v1, v4, vcc
	v_sub_u32_e32 v4, v3, v2
	v_cndmask_b32_e32 v3, v3, v4, vcc
	v_add_u32_e32 v4, 1, v1
	v_cmp_ge_u32_e32 vcc, v3, v2
	v_add_u32_e32 v3, 1, v5
	s_nop 0
	v_cndmask_b32_e32 v1, v1, v4, vcc
	v_mul_lo_u32 v4, v2, v1
	v_add_u32_e32 v2, v4, v2
	v_cmp_ne_u32_e32 vcc, v3, v2
	s_and_saveexec_b64 s[4:5], vcc
	s_xor_b64 s[4:5], exec, s[4:5]
	s_cbranch_execz .LBB0_854
	s_waitcnt lgkmcnt(0)
	v_mov_b32_e32 v0, 0x2000
	global_load_dword v0, v0, s[2:3] offset:1024 sc1
	s_add_u32 s14, s2, 0x2400
	s_addc_u32 s15, s3, 0
	s_waitcnt vmcnt(0)
	v_cmp_eq_u32_e32 vcc, v0, v1
	s_and_saveexec_b64 s[8:9], vcc
	s_cbranch_execz .LBB0_853
	s_mov_b32 s13, 1
	s_mov_b64 s[16:17], 0
	v_mov_b32_e32 v0, 0
	s_branch .LBB0_844

.LBB0_871:
	s_or_b64 exec, exec, s[4:5]
	s_mov_b64 s[4:5], exec
	v_mbcnt_lo_u32_b32 v0, s4, 0
	v_mbcnt_hi_u32_b32 v0, s5, v0
	v_cmp_eq_u32_e32 vcc, 0, v0
	s_waitcnt vmcnt(0)
	s_and_saveexec_b64 s[8:9], vcc
	s_cbranch_execz .LBB0_873
	s_bcnt1_i32_b64 s4, s[4:5]
	v_mov_b32_e32 v0, 0x2000
	v_mov_b32_e32 v1, s4
	global_atomic_add v0, v1, s[2:3] offset:1024

.LBB0_937:
	s_or_b64 exec, exec, s[8:9]
	v_cvt_f32_u32_e32 v4, v2
	s_waitcnt vmcnt(0)
	buffer_inv sc1
	v_readfirstlane_b32 s6, v3
	v_sub_u32_e32 v3, 0, v2
	v_rcp_iflag_f32_e32 v4, v4
	v_add_u32_e32 v5, s6, v1
	v_mul_f32_e32 v4, 0x4f7ffffe, v4
	v_cvt_u32_f32_e32 v4, v4
	v_mul_lo_u32 v1, v3, v4
	v_mul_hi_u32 v1, v4, v1
	v_add_u32_e32 v1, v4, v1
	v_mul_hi_u32 v1, v5, v1
	v_mul_lo_u32 v3, v1, v2
	v_sub_u32_e32 v3, v5, v3
	v_add_u32_e32 v4, 1, v1
	v_cmp_ge_u32_e32 vcc, v3, v2
	s_nop 1
	v_cndmask_b32_e32 v1, v1, v4, vcc
	v_sub_u32_e32 v4, v3, v2
	v_cndmask_b32_e32 v3, v3, v4, vcc
	v_add_u32_e32 v4, 1, v1
	v_cmp_ge_u32_e32 vcc, v3, v2
	v_add_u32_e32 v3, 1, v5
	s_nop 0
	v_cndmask_b32_e32 v1, v1, v4, vcc
	v_mul_lo_u32 v4, v2, v1
	v_add_u32_e32 v2, v4, v2
	v_cmp_ne_u32_e32 vcc, v3, v2
	s_and_saveexec_b64 s[6:7], vcc
	s_xor_b64 s[6:7], exec, s[6:7]
	s_cbranch_execz .LBB0_951
	s_waitcnt lgkmcnt(0)
	v_mov_b32_e32 v0, 0x2000
	global_load_dword v0, v0, s[4:5] offset:1024 sc1
	s_add_u32 s10, s4, 0x2400
	s_addc_u32 s11, s5, 0
	s_waitcnt vmcnt(0)
	v_cmp_eq_u32_e32 vcc, v0, v1
	s_and_saveexec_b64 s[8:9], vcc
	s_cbranch_execz .LBB0_950
	s_mov_b32 s12, 1
	s_mov_b64 s[14:15], 0
	v_mov_b32_e32 v0, 0
	s_branch .LBB0_941

.LBB0_968:
	s_or_b64 exec, exec, s[8:9]
	s_mov_b64 s[8:9], exec
	v_mbcnt_lo_u32_b32 v0, s8, 0
	v_mbcnt_hi_u32_b32 v0, s9, v0
	v_cmp_eq_u32_e32 vcc, 0, v0
	s_waitcnt vmcnt(0)
	s_and_saveexec_b64 s[10:11], vcc
	s_cbranch_execz .LBB0_970
	s_bcnt1_i32_b64 s8, s[8:9]
	v_mov_b32_e32 v0, 0x2000
	v_mov_b32_e32 v1, s8
	global_atomic_add v0, v1, s[4:5] offset:1024
